# adds: softmax row max via 8 v_max3 per query group instead of 21 max ops
# speedup vs baseline: 1.0033x; 1.0026x over previous
; __device__ __forceinline__ void attn_item(LAS unsigned char* lds, const bf16_t* z, const float* kmean, bf16_t* cat, int b, int h, int j) {
;     ...
;                 float mx = fmaxf(fmaxf(s[0][qg][0], s[0][qg][1]), fmaxf(s[0][qg][2], s[0][qg][3]));
; #pragma unroll
;                 for (int ks = 1; ks < 4; ++ks) mx = fmaxf(mx, fmaxf(fmaxf(s[ks][qg][0], s[ks][qg][1]), fmaxf(s[ks][qg][2], s[ks][qg][3])));
;                 mx = fmaxf(mx, __shfl_xor(mx, 16)); mx = fmaxf(mx, __shfl_xor(mx, 32));
;                 mx = selq ? mx : -1e30f;
;                 const float mnew = fmaxf(mrun[qg], mx); const float alpha = __builtin_amdgcn_exp2f((mrun[qg] - mnew) * SC); mrun[qg] = mnew;
;                 const float sub = selq ? (-mnew * SC) : -INFINITY;
;                 float ls = 0.f; float pv[4][4];
; #pragma unroll
;                 for (int ks = 0; ks < 4; ++ks)
; #pragma unroll
;                     for (int i = 0; i < 4; ++i) { const float pp = __builtin_amdgcn_exp2f(__builtin_fmaf(s[ks][qg][i], SC, sub)); pv[ks][i] = pp; ls += pp; }
;                 lrun[qg] = lrun[qg] * alpha + ls;
;                 if (__ballot(alpha != 1.0f) != 0ull) {
; #pragma unroll
;                     for (int ds = 0; ds < 4; ++ds) o[ds][qg] = o[ds][qg] * alpha;
.LBB0_1599:
	v_mbcnt_hi_u32_b32 v114, -1, v227
	v_and_b32_e32 v143, 64, v114
	v_xor_b32_e32 v142, 16, v114
	v_add_u32_e32 v143, 64, v143
	s_and_b64 s[2:3], s[36:37], exec
	v_cmp_lt_i32_e32 vcc, v142, v143
	v_xor_b32_e32 v144, 32, v114
	s_cselect_b32 s2, s49, s83
	v_cndmask_b32_e32 v142, v114, v142, vcc
	v_cmp_lt_i32_e32 vcc, v144, v143
	s_lshl_b32 s2, 1, s2
	v_cndmask_b32_e32 v114, v114, v144, vcc
	v_lshlrev_b32_e32 v143, 2, v114
	v_and_b32_e32 v114, s2, v106
	v_cmp_ne_u32_e32 vcc, 0, v114
	v_lshlrev_b32_e32 v142, 2, v142
	v_max3_f32 v114, v82, v83, v84
	v_max3_f32 v144, v85, v86, v87
	v_max3_f32 v145, v88, v89, v90
	v_max3_f32 v146, v91, v92, v93
	v_max3_f32 v114, v114, v94, v95
	v_max3_f32 v144, v144, v96, v97
	v_max3_f32 v114, v114, v144, v145
	v_max_f32_e32 v114, v114, v146
	ds_bpermute_b32 v144, v142, v114
	s_or_b64 s[10:11], s[36:37], vcc
	s_waitcnt lgkmcnt(0)
	v_max_f32_e32 v114, v114, v144
	ds_bpermute_b32 v144, v143, v114
	s_waitcnt lgkmcnt(0)
	v_max_f32_e32 v114, v114, v144
	v_cndmask_b32_e64 v114, v194, v114, s[10:11]
	v_max_f32_e32 v114, v110, v114
	v_sub_f32_e32 v110, v110, v114
	v_mul_f32_e32 v110, 0x3e38aa3b, v110
	v_exp_f32_e32 v110, v110
	s_nop 0
	v_cmp_neq_f32_e32 vcc, 1.0, v110
	s_cbranch_vccz .LBB0_1601
	v_pk_mul_f32 v[6:7], v[6:7], v[110:111] op_sel_hi:[1,0]
	v_pk_mul_f32 v[4:5], v[4:5], v[110:111] op_sel_hi:[1,0]
	v_pk_mul_f32 v[32:33], v[32:33], v[110:111] op_sel_hi:[1,0]
	v_pk_mul_f32 v[30:31], v[30:31], v[110:111] op_sel_hi:[1,0]
	v_pk_mul_f32 v[40:41], v[40:41], v[110:111] op_sel_hi:[1,0]
	v_pk_mul_f32 v[38:39], v[38:39], v[110:111] op_sel_hi:[1,0]
	v_pk_mul_f32 v[48:49], v[48:49], v[110:111] op_sel_hi:[1,0]
	v_pk_mul_f32 v[46:47], v[46:47], v[110:111] op_sel_hi:[1,0]

; __device__ __forceinline__ void attn_item(LAS unsigned char* lds, const bf16_t* z, const float* kmean, bf16_t* cat, int b, int h, int j) {
;     ...
;                 float mx = fmaxf(fmaxf(s[0][qg][0], s[0][qg][1]), fmaxf(s[0][qg][2], s[0][qg][3]));
; #pragma unroll
;                 for (int ks = 1; ks < 4; ++ks) mx = fmaxf(mx, fmaxf(fmaxf(s[ks][qg][0], s[ks][qg][1]), fmaxf(s[ks][qg][2], s[ks][qg][3])));
;                 mx = fmaxf(mx, __shfl_xor(mx, 16)); mx = fmaxf(mx, __shfl_xor(mx, 32));
;                 mx = selq ? mx : -1e30f;
;                 const float mnew = fmaxf(mrun[qg], mx); const float alpha = __builtin_amdgcn_exp2f((mrun[qg] - mnew) * SC); mrun[qg] = mnew;
;                 const float sub = selq ? (-mnew * SC) : -INFINITY;
;                 float ls = 0.f; float pv[4][4];
; #pragma unroll
;                 for (int ks = 0; ks < 4; ++ks)
; #pragma unroll
;                     for (int i = 0; i < 4; ++i) { const float pp = __builtin_amdgcn_exp2f(__builtin_fmaf(s[ks][qg][i], SC, sub)); pv[ks][i] = pp; ls += pp; }
;                 lrun[qg] = lrun[qg] * alpha + ls;
;                 if (__ballot(alpha != 1.0f) != 0ull) {
; #pragma unroll
;                     for (int ds = 0; ds < 4; ++ds) o[ds][qg] = o[ds][qg] * alpha;
.LBB0_1603:
	v_max3_f32 v92, v78, v79, v80
	v_max3_f32 v115, v81, v62, v63
	v_max3_f32 v132, v64, v65, v58
	v_max3_f32 v133, v59, v60, v61
	v_max3_f32 v92, v92, v74, v75
	v_max3_f32 v115, v115, v76, v77
	v_max3_f32 v92, v92, v115, v132
	v_max_f32_e32 v92, v92, v133
	ds_bpermute_b32 v115, v142, v92
	v_and_b32_e32 v132, s2, v107
	v_cmp_ne_u32_e32 vcc, 0, v132
	s_or_b64 s[8:9], s[36:37], vcc
	s_waitcnt lgkmcnt(0)
	v_max_f32_e32 v92, v92, v115
	ds_bpermute_b32 v115, v143, v92
	s_waitcnt lgkmcnt(0)
	v_max_f32_e32 v92, v92, v115
	v_cndmask_b32_e64 v92, v194, v92, s[8:9]
	v_max_f32_e32 v115, v111, v92
	v_sub_f32_e32 v92, v111, v115
	v_mul_f32_e32 v92, 0x3e38aa3b, v92
	v_exp_f32_e32 v92, v92
	s_nop 0
	v_cmp_neq_f32_e32 vcc, 1.0, v92
	s_cbranch_vccz .LBB0_1605
	v_pk_mul_f32 v[2:3], v[2:3], v[92:93] op_sel_hi:[1,0]
	v_pk_mul_f32 v[0:1], v[0:1], v[92:93] op_sel_hi:[1,0]
	v_pk_mul_f32 v[28:29], v[28:29], v[92:93] op_sel_hi:[1,0]
	v_pk_mul_f32 v[26:27], v[26:27], v[92:93] op_sel_hi:[1,0]
	v_pk_mul_f32 v[36:37], v[36:37], v[92:93] op_sel_hi:[1,0]
	v_pk_mul_f32 v[34:35], v[34:35], v[92:93] op_sel_hi:[1,0]
	v_pk_mul_f32 v[44:45], v[44:45], v[92:93] op_sel_hi:[1,0]
	v_pk_mul_f32 v[42:43], v[42:43], v[92:93] op_sel_hi:[1,0]
